# SB loop: first two V tr-reads hoisted ~30 VALU instrs ahead of PV MFMAs (operand regs v[100:103] freed early), B operands rotated
# baseline (speedup 1.0000x reference)
.LBB0_404:
	s_add_i32 s80, s80, -1
	s_cmp_lt_u32 s80, 2
	s_cselect_b64 s[34:35], -1, 0
	s_nop 1
	v_mul_f32_e32 v33, 0xbfb8aa3b, v33
	v_mul_f32_e32 v34, 0xbfb8aa3b, v34
	v_exp_f32_e32 v33, v33
	v_exp_f32_e32 v34, v34
	v_mul_f32_e32 v41, 0xbfb8aa3b, v41
	v_exp_f32_e32 v41, v41
	v_add_f32_e32 v33, 1.0, v33
	v_add_f32_e32 v96, 1.0, v34
	v_mul_f32_e32 v42, 0xbfb8aa3b, v42
	v_rcp_f32_e32 v34, v33
	v_rcp_f32_e32 v33, v96
	v_exp_f32_e32 v96, v42
	v_add_f32_e32 v41, 1.0, v41
	v_mul_f32_e32 v42, 0xbfb8aa3b, v43
	v_mul_f32_e32 v45, 0xbfb8aa3b, v45
	v_mul_f32_e32 v46, 0xbfb8aa3b, v46
	v_mul_f32_e32 v40, 0xbfb8aa3b, v40
	v_exp_f32_e32 v43, v42
	v_rcp_f32_e32 v42, v41
	v_add_f32_e32 v41, 1.0, v96
	v_mul_f32_e32 v44, 0xbfb8aa3b, v44
	v_exp_f32_e32 v45, v45
	v_exp_f32_e32 v96, v46
	v_mul_f32_e32 v46, 0xbfb8aa3b, v47
	v_exp_f32_e32 v40, v40
	v_exp_f32_e32 v44, v44
	v_exp_f32_e32 v47, v46
	v_add_f32_e32 v45, 1.0, v45
	v_add_f32_e32 v40, 1.0, v40
	v_add_f32_e32 v43, 1.0, v43
	v_add_f32_e32 v44, 1.0, v44
	v_rcp_f32_e32 v46, v45
	v_add_f32_e32 v45, 1.0, v96
	v_add_f32_e32 v47, 1.0, v47
	v_rcp_f32_e32 v40, v40
	v_rcp_f32_e32 v41, v41
	v_rcp_f32_e32 v43, v43
	v_rcp_f32_e32 v44, v44
	v_rcp_f32_e32 v45, v45
	v_rcp_f32_e32 v47, v47
	v_mul_f32_e32 v36, 0xbfb8aa3b, v36
	v_mul_f32_e32 v37, 0xbfb8aa3b, v37
	v_mul_f32_e32 v38, 0xbfb8aa3b, v38
	v_mul_f32_e32 v39, 0xbfb8aa3b, v39
	v_exp_f32_e32 v36, v36
	v_exp_f32_e32 v37, v37
	v_exp_f32_e32 v38, v38
	v_exp_f32_e32 v39, v39
	v_pk_add_f32 v[98:99], v[40:41], 1.0 op_sel_hi:[1,0] neg_lo:[1,0] neg_hi:[1,0]
	v_pk_add_f32 v[100:101], v[42:43], 1.0 op_sel_hi:[1,0] neg_lo:[1,0] neg_hi:[1,0]
	v_pk_add_f32 v[102:103], v[44:45], 1.0 op_sel_hi:[1,0] neg_lo:[1,0] neg_hi:[1,0]
	v_pk_add_f32 v[104:105], v[46:47], 1.0 op_sel_hi:[1,0] neg_lo:[1,0] neg_hi:[1,0]
	v_pk_mul_f32 v[98:99], v[98:99], v[100:101]
	v_pk_mul_f32 v[102:103], v[102:103], v[104:105]
	v_mov_b32_e32 v107, v98
	v_mov_b32_e32 v106, v102
	v_mov_b32_e32 v98, v103
	v_add_f32_e32 v36, 1.0, v36
	v_add_f32_e32 v37, 1.0, v37
	v_add_f32_e32 v97, 1.0, v38
	v_add_f32_e32 v39, 1.0, v39
	v_pk_mul_f32 v[106:107], v[106:107], v[98:99]
	v_mul_f32_e32 v32, 0xbfb8aa3b, v32
	v_mul_f32_e32 v35, 0xbfb8aa3b, v35
	v_rcp_f32_e32 v36, v36
	v_rcp_f32_e32 v38, v37
	v_rcp_f32_e32 v37, v97
	v_rcp_f32_e32 v39, v39
	ds_bpermute_b32 v167, v159, v107
	ds_bpermute_b32 v166, v159, v106
	v_exp_f32_e32 v32, v32
	v_exp_f32_e32 v35, v35
	v_pk_add_f32 v[170:171], v[36:37], 1.0 op_sel_hi:[1,0] neg_lo:[1,0] neg_hi:[1,0]
	v_pk_add_f32 v[172:173], v[38:39], 1.0 op_sel_hi:[1,0] neg_lo:[1,0] neg_hi:[1,0]
	v_add_f32_e32 v32, 1.0, v32
	v_add_f32_e32 v35, 1.0, v35
	v_pk_mul_f32 v[170:171], v[170:171], v[172:173]
	s_waitcnt lgkmcnt(0)
	v_pk_mul_f32 v[106:107], v[106:107], v[166:167]
	v_rcp_f32_e32 v32, v32
	v_rcp_f32_e32 v35, v35
	v_mov_b32_e32 v174, v170
	v_mov_b32_e32 v175, v106
	v_mov_b32_e32 v176, v171
	v_mov_b32_e32 v177, v107
	v_pk_mul_f32 v[174:175], v[174:175], v[176:177]
	ds_bpermute_b32 v177, v159, v174
	v_pk_add_f32 v[96:97], v[32:33], 1.0 op_sel_hi:[1,0] neg_lo:[1,0] neg_hi:[1,0]
	v_pk_add_f32 v[168:169], v[34:35], 1.0 op_sel_hi:[1,0] neg_lo:[1,0] neg_hi:[1,0]
	v_mov_b32_e32 v179, v174
	v_pk_mul_f32 v[96:97], v[96:97], v[168:169]
	v_mov_b32_e32 v182, v168
	v_mov_b32_e32 v178, v96
	v_mov_b32_e32 v176, v97
	s_waitcnt lgkmcnt(0)
	v_pk_mul_f32 v[178:179], v[178:179], v[176:177]
	ds_bpermute_b32 v174, v159, v178
	v_mov_b32_e32 v180, v97
	v_cndmask_b32_e64 v102, 1.0, v166, s[40:41]
	v_mov_b32_e32 v147, v104
	s_waitcnt lgkmcnt(0)
	v_pk_mul_f32 v[178:179], v[178:179], v[174:175]
	s_nop 0
	v_mul_f32_e32 v181, v146, v179
	v_cndmask_b32_e64 v183, 1.0, v174, s[40:41]
	v_pk_mul_f32 v[180:181], v[182:183], v[180:181]
	s_nop 0
	v_mul_f32_e32 v96, v180, v181
	v_mul_f32_e32 v96, v32, v96
	v_mul_f32_e32 v32, v97, v181
	v_mul_f32_e32 v97, v34, v32
	v_mul_f32_e32 v32, v169, v181
	v_mul_f32_e32 v98, v33, v32
	v_mul_f32_e32 v107, v35, v181
	v_mul_f32_e32 v33, v146, v175
	v_cndmask_b32_e64 v35, 1.0, v177, s[40:41]
	v_mov_b32_e32 v34, v172
	v_mov_b32_e32 v32, v171
	v_pk_mul_f32 v[32:33], v[34:35], v[32:33]
	v_cndmask_b32_e64 v35, 1.0, v167, s[40:41]
	v_mul_f32_e32 v32, v32, v33
	v_mul_f32_e32 v36, v36, v32
	v_mul_f32_e32 v32, v171, v33
	v_mul_f32_e32 v38, v38, v32
	v_mul_f32_e32 v32, v173, v33
	v_mul_f32_e32 v37, v37, v32
	v_mul_f32_e32 v39, v39, v33
	v_mul_f32_e32 v33, v146, v106
	v_mov_b32_e32 v34, v100
	v_mov_b32_e32 v32, v99
	v_pk_mul_f32 v[32:33], v[34:35], v[32:33]
	s_nop 0
	v_mul_f32_e32 v32, v32, v33
	v_mul_f32_e32 v40, v40, v32
	v_mul_f32_e32 v32, v99, v33
	v_mul_f32_e32 v42, v42, v32
	v_mul_f32_e32 v32, v101, v33
	ds_read_b64_tr_b16 v[100:101], v162
	v_mul_f32_e32 v41, v41, v32
	v_mul_f32_e32 v43, v43, v33
	v_pk_mul_f32 v[32:33], v[146:147], v[102:103]
	s_nop 0
	v_mul_f32_e32 v33, v32, v33
	v_mul_f32_e32 v44, v44, v33
	v_mul_f32_e32 v33, v32, v103
	ds_read_b64_tr_b16 v[102:103], v162 offset:512
	v_mul_f32_e32 v46, v46, v33
	v_mul_f32_e32 v33, v32, v105
	v_mul_f32_e32 v45, v45, v33
	v_mul_f32_e32 v47, v47, v32
	v_cvt_pk_bf16_f32 v32, v96, v97
	v_cvt_pk_bf16_f32 v33, v98, v107
	v_cvt_pk_bf16_f32 v34, v36, v38
	v_cvt_pk_bf16_f32 v35, v37, v39
	v_cvt_pk_bf16_f32 v36, v40, v42
	v_cvt_pk_bf16_f32 v37, v41, v43
	v_cvt_pk_bf16_f32 v38, v44, v46
	v_cvt_pk_bf16_f32 v39, v45, v47
	ds_read_b64_tr_b16 v[40:41], v162 offset:2048
	ds_read_b64_tr_b16 v[42:43], v162 offset:2560
	ds_read_b64_tr_b16 v[44:45], v162 offset:1024
	ds_read_b64_tr_b16 v[46:47], v162 offset:1536
	ds_read_b64_tr_b16 v[96:97], v162 offset:3072
	ds_read_b64_tr_b16 v[98:99], v162 offset:3584
	s_waitcnt lgkmcnt(6)
	v_mfma_f32_32x32x16_bf16 v[0:15], v[32:35], v[100:103], v[0:15]
	s_waitcnt lgkmcnt(4)
	v_mfma_f32_32x32x16_bf16 v[16:31], v[32:35], v[40:43], v[16:31]
	s_waitcnt lgkmcnt(2)
	v_mfma_f32_32x32x16_bf16 v[0:15], v[36:39], v[44:47], v[0:15]
	s_waitcnt lgkmcnt(0)
	v_mfma_f32_32x32x16_bf16 v[16:31], v[36:39], v[96:99], v[16:31]
	s_waitcnt vmcnt(2)
	v_mov_b64_e32 v[104:105], v[120:121]
	v_mov_b64_e32 v[100:101], v[116:117]
	v_mov_b64_e32 v[96:97], v[112:113]
	v_mul_f32_e32 v32, v178, v179
	v_mul_f32_e32 v146, v146, v32
	v_mov_b64_e32 v[32:33], v[108:109]
	v_mov_b64_e32 v[106:107], v[122:123]
	v_mov_b64_e32 v[102:103], v[118:119]
	v_mov_b64_e32 v[98:99], v[114:115]
	v_mov_b64_e32 v[34:35], v[110:111]
	s_and_b64 vcc, exec, s[34:35]
	s_cbranch_vccz .LBB0_400
